# attention QK: one LDS wait per MFMA pair (the two K-fragment waits merged) so the p0/p1 MFMAs of a d-step issue back to back
# baseline (speedup 1.0000x reference)
; #define LAS __attribute__((address_space(3)))
; __device__ __forceinline__ int crow(int r, int hi) { return (r & 3) + 8 * (r >> 2) + 4 * hi; }
; #define MFMA32(a, b, c) __builtin_amdgcn_mfma_f32_32x32x16_bf16((a), (b), (c), 0, 0, 0)
; __device__ __forceinline__ void unit(LAS unsigned char* lds, const Tensors& T, int h, int qrow0, int nact, bool sample, int limbase, int kv0, int kvnew, int nt) {
;     ...
;     for (int t = 0; t < nt; ++t) {
;         const int buf = t & 1;
;         if (t + 1 < nt) ATT_ISSUE(t + 1);
;         if (active && t <= lim) {
;             const LAS unsigned char* kp = lds + OFF_K + buf * KBUF + r32 * KP + hi * 16;
;             f32x16 p0, p1;
; #pragma unroll
;             for (int r = 0; r < 16; ++r) { p0[r] = 0.f; p1[r] = 0.f; }
;             { bf16x8 kf[4][2];
; #pragma unroll
;               for (int i = 0; i < 4; ++i) { kf[i][0] = *(const LAS bf16x8*)(kp + i * 32); kf[i][1] = *(const LAS bf16x8*)(kp + 32 * KP + i * 32); }
;               __builtin_amdgcn_sched_barrier(0);
; #pragma unroll
;               for (int i = 0; i < 12; ++i) {
;                   p0 = MFMA32(kf[i & 3][0], qf[i], p0); p1 = MFMA32(kf[i & 3][1], qf[i], p1);
;                   if (i + 4 < 12) { kf[i & 3][0] = *(const LAS bf16x8*)(kp + (i + 4) * 32); kf[i & 3][1] = *(const LAS bf16x8*)(kp + 32 * KP + (i + 4) * 32); }
;                   __builtin_amdgcn_sched_barrier(0);
;               } }
;             float rm = fmaxf(p0[0], p1[0]);
; #pragma unroll
;             for (int r = 1; r < 16; ++r) rm = fmaxf(rm, fmaxf(p0[r], p1[r]));
;             { const auto rr = __builtin_amdgcn_permlane32_swap(__float_as_uint(rm), __float_as_uint(rm), false, false);
;               rm = fmaxf(__uint_as_float(rr[0]), __uint_as_float(rr[1])); }
;             const bool need = rm > mrun + 8.0f;
;             if (__builtin_amdgcn_ballot_w64(need) != 0ull) {
;                 const float mn = need ? rm : mrun; const float alpha = __builtin_amdgcn_exp2f(mrun - mn); mrun = mn; lrun *= alpha;
;                 if (hi == 0) scr[r32] = alpha;
;                 asm volatile("s_waitcnt lgkmcnt(0)" ::: "memory");
; #pragma unroll
;                 for (int r = 0; r < 16; ++r) { const float f = scr[crow(r, hi)];
; #pragma unroll
;                     for (int d = 0; d < 4; ++d) o[d][r] *= f; }
;                 asm volatile("s_waitcnt lgkmcnt(0)" ::: "memory");
;             }
.Lat_prio:
.LBB0_904:
	s_and_b32 s16, s9, 1
	s_cmp_gt_i32 s9, s10
	s_cselect_b64 s[0:1], -1, 0
	s_or_b64 s[0:1], s[22:23], s[0:1]
	s_and_b64 vcc, exec, s[0:1]
	s_cbranch_vccnz .LBB0_909
	s_mul_i32 s0, s16, 0x6400
	v_add_u32_e32 v222, s0, v221
	ds_read_b128 v[64:67], v222
	ds_read_b128 v[224:227], v222 offset:32
	ds_read_b128 v[68:71], v222 offset:12800
	ds_read_b128 v[228:231], v222 offset:12832
	ds_read_b128 v[232:235], v222 offset:64
	ds_read_b128 v[236:239], v222 offset:96
	ds_read_b128 v[240:243], v222 offset:12864
	ds_read_b128 v[244:247], v222 offset:12896
	global_load_dwordx4 v[160:163], v[198:199], off
	global_load_dwordx4 v[156:159], v[194:195], off
	global_load_dwordx4 v[152:155], v[192:193], off
	global_load_dwordx4 v[148:151], v[204:205], off
	global_load_dwordx4 v[144:147], v[202:203], off
	s_waitcnt lgkmcnt(7)
	v_mfma_f32_32x32x16_bf16 v[80:95], v[64:67], v[140:143], 0
	ds_read_b128 v[248:251], v222 offset:128
	ds_read_b128 v[166:169], v222 offset:12928
	s_waitcnt lgkmcnt(7)
	v_mfma_f32_32x32x16_bf16 v[64:79], v[68:71], v[140:143], 0
	s_waitcnt lgkmcnt(6)
	v_mfma_f32_32x32x16_bf16 v[80:95], v[224:227], v[136:139], v[80:95]
	v_mfma_f32_32x32x16_bf16 v[64:79], v[228:231], v[136:139], v[64:79]
	ds_read_b128 v[224:227], v222 offset:160
	ds_read_b128 v[228:231], v222 offset:12960
	s_waitcnt lgkmcnt(5)
	v_mfma_f32_32x32x16_bf16 v[80:95], v[232:235], v[132:135], v[80:95]
	v_mfma_f32_32x32x16_bf16 v[64:79], v[240:243], v[132:135], v[64:79]
	ds_read_b128 v[232:235], v222 offset:192
	ds_read_b128 v[240:243], v222 offset:12992
	s_waitcnt lgkmcnt(6)
	v_mfma_f32_32x32x16_bf16 v[80:95], v[236:239], v[128:131], v[80:95]
	v_mfma_f32_32x32x16_bf16 v[64:79], v[244:247], v[128:131], v[64:79]
	ds_read_b128 v[236:239], v222 offset:224
	ds_read_b128 v[244:247], v222 offset:13024
	s_waitcnt lgkmcnt(6)
	v_mfma_f32_32x32x16_bf16 v[80:95], v[248:251], v[124:127], v[80:95]
	v_mfma_f32_32x32x16_bf16 v[64:79], v[166:169], v[124:127], v[64:79]
	ds_read_b128 v[166:169], v222 offset:256
	ds_read_b128 v[248:251], v222 offset:13056
	s_waitcnt lgkmcnt(6)
	v_mfma_f32_32x32x16_bf16 v[80:95], v[224:227], v[120:123], v[80:95]
	v_mfma_f32_32x32x16_bf16 v[64:79], v[228:231], v[120:123], v[64:79]
	ds_read_b128 v[224:227], v222 offset:288
	ds_read_b128 v[228:231], v222 offset:13088
	s_waitcnt lgkmcnt(6)
	v_mfma_f32_32x32x16_bf16 v[80:95], v[232:235], v[116:119], v[80:95]
	v_mfma_f32_32x32x16_bf16 v[64:79], v[240:243], v[116:119], v[64:79]
	ds_read_b128 v[232:235], v222 offset:320
	ds_read_b128 v[240:243], v222 offset:13120
	s_waitcnt lgkmcnt(6)
	v_mfma_f32_32x32x16_bf16 v[80:95], v[236:239], v[112:115], v[80:95]
	v_mfma_f32_32x32x16_bf16 v[64:79], v[244:247], v[112:115], v[64:79]
	ds_read_b128 v[236:239], v222 offset:352
	ds_read_b128 v[244:247], v222 offset:13152
	s_waitcnt lgkmcnt(6)
	v_mfma_f32_32x32x16_bf16 v[80:95], v[166:169], v[108:111], v[80:95]
	s_waitcnt lgkmcnt(5)
	v_mfma_f32_32x32x16_bf16 v[64:79], v[248:251], v[108:111], v[64:79]
	s_waitcnt lgkmcnt(4)
	v_mfma_f32_32x32x16_bf16 v[80:95], v[224:227], v[104:107], v[80:95]
	s_waitcnt lgkmcnt(3)
	v_mfma_f32_32x32x16_bf16 v[64:79], v[228:231], v[104:107], v[64:79]
	s_waitcnt lgkmcnt(2)
	v_mfma_f32_32x32x16_bf16 v[80:95], v[232:235], v[100:103], v[80:95]
	s_waitcnt lgkmcnt(1)
	v_mfma_f32_32x32x16_bf16 v[64:79], v[240:243], v[100:103], v[64:79]
	s_waitcnt lgkmcnt(0)
	v_mfma_f32_32x32x16_bf16 v[80:95], v[236:239], v[96:99], v[80:95]
	v_mfma_f32_32x32x16_bf16 v[64:79], v[244:247], v[96:99], v[64:79]
	s_nop 11
	v_max3_f32 v224, v64, v65, v66
	v_max3_f32 v225, v67, v68, v69
	v_max3_f32 v226, v70, v71, v72
	v_max3_f32 v227, v73, v74, v75
	v_max3_f32 v228, v76, v77, v78
	v_max3_f32 v229, v79, v80, v81
	v_max3_f32 v230, v82, v83, v84
	v_max3_f32 v231, v85, v86, v87
	v_max3_f32 v232, v88, v89, v90
	v_max3_f32 v233, v91, v92, v93
	v_max3_f32 v224, v224, v225, v226
	v_max3_f32 v227, v227, v228, v229
	v_max3_f32 v230, v230, v231, v232
	v_max3_f32 v233, v233, v94, v95
	v_max3_f32 v224, v224, v227, v230
	v_max_f32_e32 v166, v224, v233
	v_mov_b32_e32 v167, v166
	s_nop 1
	v_permlane32_swap_b32_e32 v166, v167
	v_max_f32_e32 v222, v166, v167
	v_add_f32_e32 v166, 0x41000000, v223
	v_cmp_gt_f32_e32 vcc, v222, v166
	s_cbranch_vccz .LBB0_910
	s_nop 0
	v_cndmask_b32_e32 v222, v223, v222, vcc
	v_sub_f32_e32 v166, v223, v222
	v_exp_f32_e32 v223, v166
	s_and_saveexec_b64 s[0:1], s[38:39]
	ds_write_b32 v189, v223
	s_or_b64 exec, exec, s[0:1]
	v_mul_f32_e32 v191, v191, v223
	s_waitcnt lgkmcnt(0)
	v_add_u32_e32 v223, s12, v186
	ds_read_b128 v[166:169], v223
	ds_read_b128 v[224:227], v223 offset:32
	ds_read_b128 v[228:231], v223 offset:64
	ds_read_b128 v[232:235], v223 offset:96
	s_waitcnt lgkmcnt(0)
	s_waitcnt lgkmcnt(3)
	v_pk_mul_f32 v[2:3], v[2:3], v[168:169]
	s_waitcnt lgkmcnt(2)
	v_pk_mul_f32 v[4:5], v[4:5], v[224:225]
	s_waitcnt lgkmcnt(1)
	v_pk_mul_f32 v[8:9], v[8:9], v[228:229]
	s_waitcnt lgkmcnt(0)
	v_pk_mul_f32 v[12:13], v[12:13], v[232:233]
	v_pk_mul_f32 v[14:15], v[14:15], v[234:235]
	v_pk_mul_f32 v[10:11], v[10:11], v[230:231]
	v_pk_mul_f32 v[6:7], v[6:7], v[226:227]
	v_pk_mul_f32 v[0:1], v[0:1], v[166:167]
	v_pk_mul_f32 v[60:61], v[60:61], v[232:233]
	v_pk_mul_f32 v[56:57], v[56:57], v[228:229]
	v_pk_mul_f32 v[52:53], v[52:53], v[224:225]
	v_pk_mul_f32 v[62:63], v[62:63], v[234:235]
	v_pk_mul_f32 v[58:59], v[58:59], v[230:231]
	v_pk_mul_f32 v[54:55], v[54:55], v[226:227]
	v_pk_mul_f32 v[50:51], v[50:51], v[168:169]
	v_pk_mul_f32 v[48:49], v[48:49], v[166:167]
	v_pk_mul_f32 v[44:45], v[44:45], v[232:233]
	v_pk_mul_f32 v[40:41], v[40:41], v[228:229]
	v_pk_mul_f32 v[36:37], v[36:37], v[224:225]
	v_pk_mul_f32 v[46:47], v[46:47], v[234:235]
	v_pk_mul_f32 v[42:43], v[42:43], v[230:231]
	v_pk_mul_f32 v[38:39], v[38:39], v[226:227]
	v_pk_mul_f32 v[34:35], v[34:35], v[168:169]
	v_pk_mul_f32 v[32:33], v[32:33], v[166:167]
	v_pk_mul_f32 v[28:29], v[28:29], v[232:233]
	v_pk_mul_f32 v[24:25], v[24:25], v[228:229]
	v_pk_mul_f32 v[20:21], v[20:21], v[224:225]
	v_pk_mul_f32 v[30:31], v[30:31], v[234:235]
	v_pk_mul_f32 v[26:27], v[26:27], v[230:231]
	v_pk_mul_f32 v[22:23], v[22:23], v[226:227]
	v_pk_mul_f32 v[18:19], v[18:19], v[168:169]
	v_pk_mul_f32 v[16:17], v[16:17], v[166:167]
	s_branch .LBB0_911
